# mix0 dynamic queue: 1:1 attention/gmlp interleave for the first 1536 entries, then 1280 attention, last 256 gmlp tiles as tail
# baseline (speedup 1.0000x reference)
.Lmy_m0_map:
	s_cmpk_lt_i32 s93, 0xc00
	s_cbranch_scc0 .LBB0_261
	s_mov_b32 s88, s93
	s_cmpk_ge_i32 s93, 0xb00
	s_cbranch_scc1 .Lmy_m0_mapped
	s_sub_i32 s88, s93, 0x300
	s_cmpk_ge_i32 s93, 0x600
	s_cbranch_scc1 .Lmy_m0_mapped
	s_lshr_b32 s88, s93, 1
	s_add_i32 s98, s88, 0x800
	s_bitcmp1_b32 s93, 0
	s_cselect_b32 s88, s98, s88
